# phase_in epilogue stores of h use sc1 (written through, consumers are on other XCDs) so the seam's L2 write-back has less to flush
# speedup vs baseline: 1.0100x; 1.0032x over previous
; DI int vbid() { return (int)blockIdx.x * 2 + half_(); }
; DI int vgrid() { return (int)gridDim.x * 2; }
; DI u32x4 pack8(const float* f) { u32x4 o; o.x = pack2(f[0], f[1]); o.y = pack2(f[2], f[3]); o.z = pack2(f[4], f[5]); o.w = pack2(f[6], f[7]); return o; }
; DI void lds_barrier() { asm volatile("s_waitcnt lgkmcnt(0)\n\ts_barrier" ::: "memory"); }
; DI int tid512() { int t = threadIdx.x; asm volatile("" : "+v"(t)); return t; }
; template <int AI, int BJ>
; DI void stage_q(const f32x4 (&acc)[2][2][4][2], float* Cs) {
;   const int t = tid512(), wid = t >> 6, lane = t & 63, wr = wid >> 2, wc = wid & 3, fr = lane & 15, fq = lane >> 4;
;   lds_barrier();
; #pragma unroll
;   for (int m = 0; m < 4; ++m)
; #pragma unroll
;     for (int n = 0; n < 2; ++n)
; #pragma unroll
;       for (int j = 0; j < 4; ++j) Cs[(wr * 64 + m * 16 + fq * 4 + j) * CST + wc * 32 + n * 16 + fr] = acc[AI][BJ][m][n][j];
;   lds_barrier();
; }
; DI bool xcd_tile256(int k, int NT, int& m, int& n) {
;   const int x = blockIdx.x & 7, slots = gridDim.x >> 3;
;   const int idx = (int)(blockIdx.x >> 3) + slots * k;
;   if (idx >= 16 * NT) return false;
;   const int mg = idx / (8 * NT), rem = idx - mg * 8 * NT;
;   n = rem >> 3; m = x * 16 + mg * 8 + (rem & 7);
;   return true;
; }
; DI bool xcd_tile(int k, int NT, int& m, int& n) {
;   const int x = (vbid() >> 1) & 7, slots = vgrid() >> 3;
;   const int idx = (((vbid() >> 4) << 1) | (vbid() & 1)) + slots * k;
;   if (idx >= 32 * NT) return false;
;   const int mg = idx / (8 * NT), rem = idx - mg * 8 * NT;
;   n = rem >> 3; m = x * 32 + mg * 8 + (rem & 7);
;   return true;
; }
; template <int AI, int BJ>
; DI void in_quadrant(PREF p, const f32x4 (&acc)[2][2][4][2], int mt, int nt, float* Cs) {
;   const int t = tid512();
;   const int row0 = mt * 256 + AI * 128, col0 = nt * 256 + BJ * 128;
;   if (col0 >= HW) return;
;   stage_q<AI, BJ>(acc, Cs);
; #pragma unroll
;   for (int q = 0; q < 4; ++q) {
;     int r = (t >> 4) + 32 * q, c = (t & 15) * 8;
;     if (col0 + c < HW) {
;       float v[8]; ld8(Cs + r * CST + c, v);
;       *(u32x4*)(p.hb + (size_t)(row0 + r) * HW + col0 + c) = pack8(v);
;     }
;   }
.LBB0_456:
	s_or_b64 exec, exec, s[18:19]
	s_lshl_b32 s17, s16, 8
	s_lshl_b32 s18, s14, 8
	s_cmp_lt_i32 s14, 11
	v_mov_b32_e32 v130, v168
	s_cselect_b64 s[20:21], -1, 0
	s_cmp_gt_i32 s14, 10
	s_cbranch_scc1 .LBB0_463
	v_mov_b32_e32 v0, v168
	s_waitcnt lgkmcnt(0)
	s_barrier
	s_nop 0
	v_and_b32_e32 v131, 15, v0
	v_lshrrev_b32_e32 v132, 2, v0
	v_lshlrev_b32_e32 v0, 1, v0
	v_lshlrev_b32_e32 v131, 2, v131
	v_and_b32_e32 v132, 0xfffffcc, v132
	v_and_or_b32 v0, v0, s89, v131
	v_mad_u64_u32 v[132:133], s[0:1], v132, s92, v[0:1]
	v_add_u32_e32 v0, 0x400, v132
	ds_write2_b32 v132, v118, v126 offset1:16
	ds_write2_b32 v132, v119, v127 offset0:132 offset1:148
	ds_write2_b32 v0, v120, v128 offset0:8 offset1:24
	ds_write2_b32 v0, v121, v129 offset0:140 offset1:156
	v_add_u32_e32 v0, 0x2000, v132
	ds_write2_b32 v0, v114, v122 offset0:64 offset1:80
	ds_write2_b32 v0, v115, v123 offset0:196 offset1:212
	v_add_u32_e32 v0, 0x2400, v132
	ds_write2_b32 v0, v116, v124 offset0:72 offset1:88
	ds_write2_b32 v0, v117, v125 offset0:204 offset1:220
	v_add_u32_e32 v0, 0x4000, v132
	ds_write2_b32 v0, v106, v110 offset0:128 offset1:144
	v_add_u32_e32 v0, 0x4400, v132
	ds_write2_b32 v0, v107, v111 offset0:4 offset1:20
	ds_write2_b32 v0, v108, v112 offset0:136 offset1:152
	v_add_u32_e32 v0, 0x4800, v132
	ds_write2_b32 v0, v109, v113 offset0:12 offset1:28
	v_add_u32_e32 v0, 0x6000, v132
	ds_write2_b32 v0, v98, v102 offset0:192 offset1:208
	v_add_u32_e32 v0, 0x6400, v132
	ds_write2_b32 v0, v99, v103 offset0:68 offset1:84
	ds_write2_b32 v0, v100, v104 offset0:200 offset1:216
	v_add_u32_e32 v0, 0x6800, v132
	ds_write2_b32 v0, v101, v105 offset0:76 offset1:92
	v_lshlrev_b32_e32 v0, 3, v130
	s_waitcnt lgkmcnt(0)
	s_barrier
	v_and_b32_e32 v98, 0x78, v0
	v_or_b32_e32 v0, s18, v98
	v_cmp_gt_i32_e32 vcc, s58, v0
	s_and_saveexec_b64 s[22:23], vcc
	s_cbranch_execz .LBB0_459
	s_ashr_i32 s19, s18, 31
	s_lshl_b64 s[0:1], s[18:19], 1
	s_add_u32 s0, s10, s0
	s_addc_u32 s1, s11, s1
	v_lshlrev_b32_e32 v0, 1, v98
	v_lshl_add_u64 v[106:107], s[0:1], 0, v[0:1]
	v_ashrrev_i32_e32 v0, 4, v130
	v_mul_lo_u32 v99, v0, s92
	v_lshl_add_u32 v108, v98, 2, v99
	s_waitcnt vmcnt(0)
	ds_read_b128 v[98:101], v108
	ds_read_b128 v[102:105], v108 offset:16
	v_add_u32_e32 v0, s17, v0
	s_waitcnt lgkmcnt(1)
	v_cvt_pk_bf16_f32 v98, v98, v99
	v_cvt_pk_bf16_f32 v99, v100, v101
	s_waitcnt lgkmcnt(0)
	v_cvt_pk_bf16_f32 v100, v102, v103
	v_mad_i64_i32 v[102:103], s[0:1], v0, s60, v[106:107]
	v_cvt_pk_bf16_f32 v101, v104, v105
	global_store_dwordx4 v[102:103], v[98:101], off sc1
	ds_read_b128 v[98:101], v108 offset:16896
	ds_read_b128 v[102:105], v108 offset:16912
	s_waitcnt lgkmcnt(1)
	v_cvt_pk_bf16_f32 v98, v98, v99
	v_cvt_pk_bf16_f32 v99, v100, v101
	s_waitcnt lgkmcnt(0)
	v_cvt_pk_bf16_f32 v100, v102, v103
	v_add_u32_e32 v102, 32, v0
	v_mad_i64_i32 v[102:103], s[0:1], v102, s60, v[106:107]
	v_cvt_pk_bf16_f32 v101, v104, v105
	global_store_dwordx4 v[102:103], v[98:101], off sc1
	ds_read_b128 v[98:101], v108 offset:33792
	ds_read_b128 v[102:105], v108 offset:33808
	s_waitcnt lgkmcnt(1)
	v_cvt_pk_bf16_f32 v98, v98, v99
	v_cvt_pk_bf16_f32 v99, v100, v101
	s_waitcnt lgkmcnt(0)
	v_cvt_pk_bf16_f32 v100, v102, v103
	v_add_u32_e32 v102, 64, v0
	v_mad_i64_i32 v[102:103], s[0:1], v102, s60, v[106:107]
	v_cvt_pk_bf16_f32 v101, v104, v105
	global_store_dwordx4 v[102:103], v[98:101], off sc1
	ds_read_b128 v[98:101], v108 offset:50688
	ds_read_b128 v[102:105], v108 offset:50704
	v_add_u32_e32 v0, 0x60, v0
	s_waitcnt lgkmcnt(1)
	v_cvt_pk_bf16_f32 v98, v98, v99
	v_cvt_pk_bf16_f32 v99, v100, v101
	s_waitcnt lgkmcnt(0)
	v_cvt_pk_bf16_f32 v100, v102, v103
	v_mad_i64_i32 v[102:103], s[0:1], v0, s60, v[106:107]
	v_cvt_pk_bf16_f32 v101, v104, v105
	global_store_dwordx4 v[102:103], v[98:101], off sc1
; DI u32x4 pack8(const float* f) { u32x4 o; o.x = pack2(f[0], f[1]); o.y = pack2(f[2], f[3]); o.z = pack2(f[4], f[5]); o.w = pack2(f[6], f[7]); return o; }
; template <int AI, int BJ>
; DI void in_quadrant(PREF p, const f32x4 (&acc)[2][2][4][2], int mt, int nt, float* Cs) {
;     ...
;   if (col0 + 128 > OFF_SV && col0 < OFF_SV + 128) {
;     int b = row0 >> 12, s0 = row0 & 4095;
; #pragma unroll
;     for (int q = 0; q < 4; ++q) {
;       int item = t + 512 * q; int c = item & 127, rg = item >> 7;
;       int vc = col0 + c - OFF_SV;
;       if (vc >= 0 && vc < 128) {
;         float v[8];
; #pragma unroll
;         for (int j = 0; j < 8; ++j) v[j] = Cs[(rg * 8 + j) * CST + c];
;         *(u32x4*)(p.Vst + ((size_t)(b * 2 + (vc >> 6)) * 64 + (vc & 63)) * S_ + s0 + rg * 8) = pack8(v);
;       }
;     }
;   }
.LBB0_459:
	s_or_b64 exec, exec, s[22:23]
	s_cmp_lt_i32 s14, 9
	s_cselect_b64 s[0:1], -1, 0
	s_cmp_eq_u32 s14, 10
	s_cselect_b64 s[22:23], -1, 0
	s_or_b64 s[0:1], s[0:1], s[22:23]
	s_and_b64 vcc, exec, s[0:1]
	s_cbranch_vccnz .LBB0_463
	v_and_b32_e32 v100, 0x7f, v130
	v_or_b32_e32 v0, s18, v100
	v_add_u32_e32 v0, 0xfffff6e0, v0
	v_cmp_gt_u32_e32 vcc, s93, v0
	s_and_saveexec_b64 s[22:23], vcc
	s_cbranch_execz .LBB0_462
	v_lshrrev_b32_e32 v98, 6, v0
	s_ashr_i32 s0, s16, 3
	v_and_or_b32 v98, s0, -2, v98
	v_ashrrev_i32_e32 v99, 31, v98
	v_lshlrev_b64 v[98:99], 19, v[98:99]
	v_lshlrev_b32_e32 v0, 13, v0
	v_lshl_add_u64 v[98:99], s[12:13], 0, v[98:99]
	v_and_b32_e32 v0, 0x7e000, v0
	v_lshl_add_u64 v[98:99], v[98:99], 0, v[0:1]
	v_lshlrev_b32_e32 v0, 2, v100
	v_ashrrev_i32_e32 v100, 4, v130
	s_and_b32 s0, s17, 0xf00
	v_and_b32_e32 v104, -8, v100
	s_lshl_b32 s52, s0, 1
	v_mad_u64_u32 v[106:107], s[0:1], v104, s92, v[0:1]
	v_or_b32_e32 v100, 7, v100
	v_mad_u64_u32 v[108:109], s[0:1], v100, s92, v[0:1]
	ds_read2_b32 v[100:101], v106 offset1:132
	s_waitcnt lgkmcnt(0)
	v_cvt_pk_bf16_f32 v100, v100, v101
	v_add_u32_e32 v101, 0x400, v106
	ds_read2_b32 v[102:103], v101 offset0:8 offset1:140
	s_waitcnt lgkmcnt(0)
	v_cvt_pk_bf16_f32 v101, v102, v103
	v_add_u32_e32 v102, 0x800, v106
	ds_read2_b32 v[102:103], v102 offset0:16 offset1:148
	s_waitcnt lgkmcnt(0)
	v_cvt_pk_bf16_f32 v102, v102, v103
	ds_read_b32 v103, v106 offset:3168
	ds_read_b32 v105, v108
	v_lshl_add_u64 v[98:99], v[98:99], 0, s[52:53]
	s_waitcnt lgkmcnt(0)
	v_cvt_pk_bf16_f32 v103, v103, v105
	v_ashrrev_i32_e32 v105, 31, v104
	v_lshl_add_u64 v[104:105], v[104:105], 1, v[98:99]
	global_store_dwordx4 v[104:105], v[100:103], off sc1
	s_nop 1
	v_add_u32_e32 v100, 0x200, v130
	v_ashrrev_i32_e32 v100, 4, v100
	v_and_b32_e32 v104, -8, v100
	v_mad_u64_u32 v[106:107], s[0:1], v104, s92, v[0:1]
	v_or_b32_e32 v100, 7, v100
	v_mad_u64_u32 v[108:109], s[0:1], v100, s92, v[0:1]
	ds_read2_b32 v[100:101], v106 offset1:132
	s_waitcnt lgkmcnt(0)
	v_cvt_pk_bf16_f32 v100, v100, v101
	v_add_u32_e32 v101, 0x400, v106
	ds_read2_b32 v[102:103], v101 offset0:8 offset1:140
	s_waitcnt lgkmcnt(0)
	v_cvt_pk_bf16_f32 v101, v102, v103
	v_add_u32_e32 v102, 0x800, v106
	ds_read2_b32 v[102:103], v102 offset0:16 offset1:148
	s_waitcnt lgkmcnt(0)
	v_cvt_pk_bf16_f32 v102, v102, v103
	ds_read_b32 v103, v106 offset:3168
	ds_read_b32 v105, v108
	s_waitcnt lgkmcnt(0)
	v_cvt_pk_bf16_f32 v103, v103, v105
	v_ashrrev_i32_e32 v105, 31, v104
	v_lshl_add_u64 v[104:105], v[104:105], 1, v[98:99]
	global_store_dwordx4 v[104:105], v[100:103], off sc1
	s_nop 1
	v_add_u32_e32 v100, 0x400, v130
	v_ashrrev_i32_e32 v100, 4, v100
	v_and_b32_e32 v104, -8, v100
	v_mad_u64_u32 v[106:107], s[0:1], v104, s92, v[0:1]
	v_or_b32_e32 v100, 7, v100
	v_mad_u64_u32 v[108:109], s[0:1], v100, s92, v[0:1]
	ds_read2_b32 v[100:101], v106 offset1:132
	s_waitcnt lgkmcnt(0)
	v_cvt_pk_bf16_f32 v100, v100, v101
	v_add_u32_e32 v101, 0x400, v106
	ds_read2_b32 v[102:103], v101 offset0:8 offset1:140
	s_waitcnt lgkmcnt(0)
	v_cvt_pk_bf16_f32 v101, v102, v103
	v_add_u32_e32 v102, 0x800, v106
	ds_read2_b32 v[102:103], v102 offset0:16 offset1:148
	s_waitcnt lgkmcnt(0)
	v_cvt_pk_bf16_f32 v102, v102, v103
	ds_read_b32 v103, v106 offset:3168
	ds_read_b32 v105, v108
	s_waitcnt lgkmcnt(0)
	v_cvt_pk_bf16_f32 v103, v103, v105
	v_ashrrev_i32_e32 v105, 31, v104
	v_lshl_add_u64 v[104:105], v[104:105], 1, v[98:99]
	global_store_dwordx4 v[104:105], v[100:103], off sc1
	s_nop 1
	v_add_u32_e32 v100, 0x600, v130
	v_ashrrev_i32_e32 v100, 4, v100
	v_and_b32_e32 v104, -8, v100
	v_mad_u64_u32 v[106:107], s[0:1], v104, s92, v[0:1]
	v_or_b32_e32 v100, 7, v100
	v_mad_u64_u32 v[108:109], s[0:1], v100, s92, v[0:1]
	v_add_u32_e32 v0, 0x400, v106
	ds_read2_b32 v[100:101], v106 offset1:132
	ds_read2_b32 v[102:103], v0 offset0:8 offset1:140
	v_add_u32_e32 v0, 0x800, v106
	s_waitcnt lgkmcnt(0)
	v_cvt_pk_bf16_f32 v100, v100, v101
	v_cvt_pk_bf16_f32 v101, v102, v103
	ds_read2_b32 v[102:103], v0 offset0:16 offset1:148
	s_waitcnt lgkmcnt(0)
	v_cvt_pk_bf16_f32 v102, v102, v103
	ds_read_b32 v0, v106 offset:3168
	ds_read_b32 v103, v108
	v_ashrrev_i32_e32 v105, 31, v104
	v_lshl_add_u64 v[98:99], v[104:105], 1, v[98:99]
	s_waitcnt lgkmcnt(0)
	v_cvt_pk_bf16_f32 v103, v0, v103
	global_store_dwordx4 v[98:99], v[100:103], off sc1

; DI u32x4 pack8(const float* f) { u32x4 o; o.x = pack2(f[0], f[1]); o.y = pack2(f[2], f[3]); o.z = pack2(f[4], f[5]); o.w = pack2(f[6], f[7]); return o; }
; DI int tid512() { int t = threadIdx.x; asm volatile("" : "+v"(t)); return t; }
; template <int AI, int BJ>
; DI void in_quadrant(PREF p, const f32x4 (&acc)[2][2][4][2], int mt, int nt, float* Cs) {
;   const int t = tid512();
;   const int row0 = mt * 256 + AI * 128, col0 = nt * 256 + BJ * 128;
;   if (col0 >= HW) return;
;   stage_q<AI, BJ>(acc, Cs);
; #pragma unroll
;   for (int q = 0; q < 4; ++q) {
;     int r = (t >> 4) + 32 * q, c = (t & 15) * 8;
;     if (col0 + c < HW) {
;       float v[8]; ld8(Cs + r * CST + c, v);
;       *(u32x4*)(p.hb + (size_t)(row0 + r) * HW + col0 + c) = pack8(v);
;     }
;   }
.LBB0_463:
	s_or_b32 s15, s18, 0x80
	s_cmpk_lt_i32 s15, 0xaa0
	v_mov_b32_e32 v98, v168
	s_cselect_b64 s[22:23], -1, 0
	s_cmpk_gt_i32 s15, 0xa9f
	s_cbranch_scc1 .LBB0_470
	v_mov_b32_e32 v0, v168
	s_waitcnt lgkmcnt(0)
	s_barrier
	s_nop 0
	v_and_b32_e32 v99, 15, v0
	v_lshrrev_b32_e32 v100, 2, v0
	v_lshlrev_b32_e32 v0, 1, v0
	v_lshlrev_b32_e32 v99, 2, v99
	v_and_b32_e32 v100, 0xfffffcc, v100
	v_and_or_b32 v0, v0, s89, v99
	v_mad_u64_u32 v[100:101], s[0:1], v100, s92, v[0:1]
	v_add_u32_e32 v0, 0x400, v100
	ds_write2_b32 v100, v86, v94 offset1:16
	ds_write2_b32 v100, v87, v95 offset0:132 offset1:148
	ds_write2_b32 v0, v88, v96 offset0:8 offset1:24
	ds_write2_b32 v0, v89, v97 offset0:140 offset1:156
	v_add_u32_e32 v0, 0x2000, v100
	ds_write2_b32 v0, v82, v90 offset0:64 offset1:80
	ds_write2_b32 v0, v83, v91 offset0:196 offset1:212
	v_add_u32_e32 v0, 0x2400, v100
	ds_write2_b32 v0, v84, v92 offset0:72 offset1:88
	ds_write2_b32 v0, v85, v93 offset0:204 offset1:220
	v_add_u32_e32 v0, 0x4000, v100
	ds_write2_b32 v0, v74, v78 offset0:128 offset1:144
	v_add_u32_e32 v0, 0x4400, v100
	ds_write2_b32 v0, v75, v79 offset0:4 offset1:20
	ds_write2_b32 v0, v76, v80 offset0:136 offset1:152
	v_add_u32_e32 v0, 0x4800, v100
	ds_write2_b32 v0, v77, v81 offset0:12 offset1:28
	v_add_u32_e32 v0, 0x6000, v100
	ds_write2_b32 v0, v66, v70 offset0:192 offset1:208
	v_add_u32_e32 v0, 0x6400, v100
	ds_write2_b32 v0, v67, v71 offset0:68 offset1:84
	ds_write2_b32 v0, v68, v72 offset0:200 offset1:216
	v_add_u32_e32 v0, 0x6800, v100
	ds_write2_b32 v0, v69, v73 offset0:76 offset1:92
	v_lshlrev_b32_e32 v0, 3, v98
	s_waitcnt lgkmcnt(0)
	s_barrier
	v_and_b32_e32 v66, 0x78, v0
	v_or_b32_e32 v0, s15, v66
	v_cmp_gt_i32_e32 vcc, s58, v0
	s_and_saveexec_b64 s[24:25], vcc
	s_cbranch_execz .LBB0_466
	s_ashr_i32 s19, s18, 31
	s_lshl_b64 s[0:1], s[18:19], 1
	s_add_u32 s0, s10, s0
	s_addc_u32 s1, s11, s1
	v_lshlrev_b32_e32 v0, 1, v66
	v_lshl_add_u64 v[74:75], s[0:1], 0, v[0:1]
	v_ashrrev_i32_e32 v0, 4, v98
	v_mul_lo_u32 v67, v0, s92
	v_lshl_add_u32 v76, v66, 2, v67
	s_waitcnt vmcnt(0)
	ds_read_b128 v[66:69], v76
	ds_read_b128 v[70:73], v76 offset:16
	v_add_u32_e32 v0, s17, v0
	s_waitcnt lgkmcnt(1)
	v_cvt_pk_bf16_f32 v66, v66, v67
	v_cvt_pk_bf16_f32 v67, v68, v69
	s_waitcnt lgkmcnt(0)
	v_cvt_pk_bf16_f32 v68, v70, v71
	v_mad_i64_i32 v[70:71], s[0:1], v0, s60, v[74:75]
	v_cvt_pk_bf16_f32 v69, v72, v73
	global_store_dwordx4 v[70:71], v[66:69], off offset:256 sc1
	ds_read_b128 v[66:69], v76 offset:16896
	ds_read_b128 v[70:73], v76 offset:16912
	s_waitcnt lgkmcnt(1)
	v_cvt_pk_bf16_f32 v66, v66, v67
	v_cvt_pk_bf16_f32 v67, v68, v69
	s_waitcnt lgkmcnt(0)
	v_cvt_pk_bf16_f32 v68, v70, v71
	v_add_u32_e32 v70, 32, v0
	v_mad_i64_i32 v[70:71], s[0:1], v70, s60, v[74:75]
	v_cvt_pk_bf16_f32 v69, v72, v73
	global_store_dwordx4 v[70:71], v[66:69], off offset:256 sc1
	ds_read_b128 v[66:69], v76 offset:33792
	ds_read_b128 v[70:73], v76 offset:33808
	s_waitcnt lgkmcnt(1)
	v_cvt_pk_bf16_f32 v66, v66, v67
	v_cvt_pk_bf16_f32 v67, v68, v69
	s_waitcnt lgkmcnt(0)
	v_cvt_pk_bf16_f32 v68, v70, v71
	v_add_u32_e32 v70, 64, v0
	v_mad_i64_i32 v[70:71], s[0:1], v70, s60, v[74:75]
	v_cvt_pk_bf16_f32 v69, v72, v73
	global_store_dwordx4 v[70:71], v[66:69], off offset:256 sc1
	ds_read_b128 v[66:69], v76 offset:50688
	ds_read_b128 v[70:73], v76 offset:50704
	v_add_u32_e32 v0, 0x60, v0
	s_waitcnt lgkmcnt(1)
	v_cvt_pk_bf16_f32 v66, v66, v67
	v_cvt_pk_bf16_f32 v67, v68, v69
	s_waitcnt lgkmcnt(0)
	v_cvt_pk_bf16_f32 v68, v70, v71
	v_mad_i64_i32 v[70:71], s[0:1], v0, s60, v[74:75]
	v_cvt_pk_bf16_f32 v69, v72, v73
	global_store_dwordx4 v[70:71], v[66:69], off offset:256 sc1
; DI u32x4 pack8(const float* f) { u32x4 o; o.x = pack2(f[0], f[1]); o.y = pack2(f[2], f[3]); o.z = pack2(f[4], f[5]); o.w = pack2(f[6], f[7]); return o; }
; template <int AI, int BJ>
; DI void in_quadrant(PREF p, const f32x4 (&acc)[2][2][4][2], int mt, int nt, float* Cs) {
;     ...
;   if (col0 + 128 > OFF_SV && col0 < OFF_SV + 128) {
;     int b = row0 >> 12, s0 = row0 & 4095;
; #pragma unroll
;     for (int q = 0; q < 4; ++q) {
;       int item = t + 512 * q; int c = item & 127, rg = item >> 7;
;       int vc = col0 + c - OFF_SV;
;       if (vc >= 0 && vc < 128) {
;         float v[8];
; #pragma unroll
;         for (int j = 0; j < 8; ++j) v[j] = Cs[(rg * 8 + j) * CST + c];
;         *(u32x4*)(p.Vst + ((size_t)(b * 2 + (vc >> 6)) * 64 + (vc & 63)) * S_ + s0 + rg * 8) = pack8(v);
;       }
;     }
;   }
.LBB0_466:
	s_or_b64 exec, exec, s[24:25]
	s_cmp_lt_i32 s14, 9
	s_cselect_b64 s[0:1], -1, 0
	s_cmpk_gt_i32 s15, 0x99f
	s_cselect_b64 s[24:25], -1, 0
	s_or_b64 s[0:1], s[0:1], s[24:25]
	s_and_b64 vcc, exec, s[0:1]
	s_cbranch_vccnz .LBB0_470
	v_and_b32_e32 v68, 0x7f, v98
	v_or_b32_e32 v0, s15, v68
	v_add_u32_e32 v0, 0xfffff6e0, v0
	v_cmp_gt_u32_e32 vcc, s93, v0
	s_and_saveexec_b64 s[24:25], vcc
	s_cbranch_execz .LBB0_469
	v_lshrrev_b32_e32 v66, 6, v0
	s_ashr_i32 s0, s16, 3
	v_and_or_b32 v66, s0, -2, v66
	v_ashrrev_i32_e32 v67, 31, v66
	v_lshlrev_b64 v[66:67], 19, v[66:67]
	v_lshlrev_b32_e32 v0, 13, v0
	v_lshl_add_u64 v[66:67], s[12:13], 0, v[66:67]
	v_and_b32_e32 v0, 0x7e000, v0
	v_lshl_add_u64 v[66:67], v[66:67], 0, v[0:1]
	v_lshlrev_b32_e32 v0, 2, v68
	v_ashrrev_i32_e32 v68, 4, v98
	s_and_b32 s0, s17, 0xf00
	v_and_b32_e32 v72, -8, v68
	s_lshl_b32 s52, s0, 1
	v_mad_u64_u32 v[74:75], s[0:1], v72, s92, v[0:1]
	v_or_b32_e32 v68, 7, v68
	v_mad_u64_u32 v[76:77], s[0:1], v68, s92, v[0:1]
	ds_read2_b32 v[68:69], v74 offset1:132
	s_waitcnt lgkmcnt(0)
	v_cvt_pk_bf16_f32 v68, v68, v69
	v_add_u32_e32 v69, 0x400, v74
	ds_read2_b32 v[70:71], v69 offset0:8 offset1:140
	s_waitcnt lgkmcnt(0)
	v_cvt_pk_bf16_f32 v69, v70, v71
	v_add_u32_e32 v70, 0x800, v74
	ds_read2_b32 v[70:71], v70 offset0:16 offset1:148
	s_waitcnt lgkmcnt(0)
	v_cvt_pk_bf16_f32 v70, v70, v71
	ds_read_b32 v71, v74 offset:3168
	ds_read_b32 v73, v76
	v_lshl_add_u64 v[66:67], v[66:67], 0, s[52:53]
	s_waitcnt lgkmcnt(0)
	v_cvt_pk_bf16_f32 v71, v71, v73
	v_ashrrev_i32_e32 v73, 31, v72
	v_lshl_add_u64 v[72:73], v[72:73], 1, v[66:67]
	global_store_dwordx4 v[72:73], v[68:71], off sc1
	s_nop 1
	v_add_u32_e32 v68, 0x200, v98
	v_ashrrev_i32_e32 v68, 4, v68
	v_and_b32_e32 v72, -8, v68
	v_mad_u64_u32 v[74:75], s[0:1], v72, s92, v[0:1]
	v_or_b32_e32 v68, 7, v68
	v_mad_u64_u32 v[76:77], s[0:1], v68, s92, v[0:1]
	ds_read2_b32 v[68:69], v74 offset1:132
	s_waitcnt lgkmcnt(0)
	v_cvt_pk_bf16_f32 v68, v68, v69
	v_add_u32_e32 v69, 0x400, v74
	ds_read2_b32 v[70:71], v69 offset0:8 offset1:140
	s_waitcnt lgkmcnt(0)
	v_cvt_pk_bf16_f32 v69, v70, v71
	v_add_u32_e32 v70, 0x800, v74
	ds_read2_b32 v[70:71], v70 offset0:16 offset1:148
	s_waitcnt lgkmcnt(0)
	v_cvt_pk_bf16_f32 v70, v70, v71
	ds_read_b32 v71, v74 offset:3168
	ds_read_b32 v73, v76
	s_waitcnt lgkmcnt(0)
	v_cvt_pk_bf16_f32 v71, v71, v73
	v_ashrrev_i32_e32 v73, 31, v72
	v_lshl_add_u64 v[72:73], v[72:73], 1, v[66:67]
	global_store_dwordx4 v[72:73], v[68:71], off sc1
	s_nop 1
	v_add_u32_e32 v68, 0x400, v98
	v_ashrrev_i32_e32 v68, 4, v68
	v_and_b32_e32 v72, -8, v68
	v_mad_u64_u32 v[74:75], s[0:1], v72, s92, v[0:1]
	v_or_b32_e32 v68, 7, v68
	v_mad_u64_u32 v[76:77], s[0:1], v68, s92, v[0:1]
	ds_read2_b32 v[68:69], v74 offset1:132
	s_waitcnt lgkmcnt(0)
	v_cvt_pk_bf16_f32 v68, v68, v69
	v_add_u32_e32 v69, 0x400, v74
	ds_read2_b32 v[70:71], v69 offset0:8 offset1:140
	s_waitcnt lgkmcnt(0)
	v_cvt_pk_bf16_f32 v69, v70, v71
	v_add_u32_e32 v70, 0x800, v74
	ds_read2_b32 v[70:71], v70 offset0:16 offset1:148
	s_waitcnt lgkmcnt(0)
	v_cvt_pk_bf16_f32 v70, v70, v71
	ds_read_b32 v71, v74 offset:3168
	ds_read_b32 v73, v76
	s_waitcnt lgkmcnt(0)
	v_cvt_pk_bf16_f32 v71, v71, v73
	v_ashrrev_i32_e32 v73, 31, v72
	v_lshl_add_u64 v[72:73], v[72:73], 1, v[66:67]
	global_store_dwordx4 v[72:73], v[68:71], off sc1
	s_nop 1
	v_add_u32_e32 v68, 0x600, v98
	v_ashrrev_i32_e32 v68, 4, v68
	v_and_b32_e32 v72, -8, v68
	v_mad_u64_u32 v[74:75], s[0:1], v72, s92, v[0:1]
	v_or_b32_e32 v68, 7, v68
	v_mad_u64_u32 v[76:77], s[0:1], v68, s92, v[0:1]
	v_add_u32_e32 v0, 0x400, v74
	ds_read2_b32 v[68:69], v74 offset1:132
	ds_read2_b32 v[70:71], v0 offset0:8 offset1:140
	v_add_u32_e32 v0, 0x800, v74
	s_waitcnt lgkmcnt(0)
	v_cvt_pk_bf16_f32 v68, v68, v69
	v_cvt_pk_bf16_f32 v69, v70, v71
	ds_read2_b32 v[70:71], v0 offset0:16 offset1:148
	s_waitcnt lgkmcnt(0)
	v_cvt_pk_bf16_f32 v70, v70, v71
	ds_read_b32 v0, v74 offset:3168
	ds_read_b32 v71, v76
	v_ashrrev_i32_e32 v73, 31, v72
	v_lshl_add_u64 v[66:67], v[72:73], 1, v[66:67]
	s_waitcnt lgkmcnt(0)
	v_cvt_pk_bf16_f32 v71, v0, v71
	global_store_dwordx4 v[66:67], v[68:71], off sc1

; DI u32x4 pack8(const float* f) { u32x4 o; o.x = pack2(f[0], f[1]); o.y = pack2(f[2], f[3]); o.z = pack2(f[4], f[5]); o.w = pack2(f[6], f[7]); return o; }
; DI int tid512() { int t = threadIdx.x; asm volatile("" : "+v"(t)); return t; }
; template <int AI, int BJ>
; DI void in_quadrant(PREF p, const f32x4 (&acc)[2][2][4][2], int mt, int nt, float* Cs) {
;   const int t = tid512();
;   const int row0 = mt * 256 + AI * 128, col0 = nt * 256 + BJ * 128;
;   if (col0 >= HW) return;
;   stage_q<AI, BJ>(acc, Cs);
; #pragma unroll
;   for (int q = 0; q < 4; ++q) {
;     int r = (t >> 4) + 32 * q, c = (t & 15) * 8;
;     if (col0 + c < HW) {
;       float v[8]; ld8(Cs + r * CST + c, v);
;       *(u32x4*)(p.hb + (size_t)(row0 + r) * HW + col0 + c) = pack8(v);
;     }
;   }
.LBB0_470:
	v_mov_b32_e32 v66, v168
	s_andn2_b64 vcc, exec, s[20:21]
	s_bitset1_b32 s17, 7
	s_cbranch_vccnz .LBB0_477
	v_mov_b32_e32 v0, v168
	s_waitcnt lgkmcnt(0)
	s_barrier
	s_nop 0
	v_and_b32_e32 v67, 15, v0
	v_lshrrev_b32_e32 v68, 2, v0
	v_lshlrev_b32_e32 v0, 1, v0
	v_lshlrev_b32_e32 v67, 2, v67
	v_and_b32_e32 v68, 0xfffffcc, v68
	v_and_or_b32 v0, v0, s89, v67
	v_mad_u64_u32 v[68:69], s[0:1], v68, s92, v[0:1]
	v_add_u32_e32 v0, 0x400, v68
	ds_write2_b32 v68, v54, v62 offset1:16
	ds_write2_b32 v68, v55, v63 offset0:132 offset1:148
	ds_write2_b32 v0, v56, v64 offset0:8 offset1:24
	ds_write2_b32 v0, v57, v65 offset0:140 offset1:156
	v_add_u32_e32 v0, 0x2000, v68
	ds_write2_b32 v0, v50, v58 offset0:64 offset1:80
	ds_write2_b32 v0, v51, v59 offset0:196 offset1:212
	v_add_u32_e32 v0, 0x2400, v68
	ds_write2_b32 v0, v52, v60 offset0:72 offset1:88
	ds_write2_b32 v0, v53, v61 offset0:204 offset1:220
	v_add_u32_e32 v0, 0x4000, v68
	ds_write2_b32 v0, v42, v46 offset0:128 offset1:144
	v_add_u32_e32 v0, 0x4400, v68
	ds_write2_b32 v0, v43, v47 offset0:4 offset1:20
	ds_write2_b32 v0, v44, v48 offset0:136 offset1:152
	v_add_u32_e32 v0, 0x4800, v68
	ds_write2_b32 v0, v45, v49 offset0:12 offset1:28
	v_add_u32_e32 v0, 0x6000, v68
	ds_write2_b32 v0, v34, v38 offset0:192 offset1:208
	v_add_u32_e32 v0, 0x6400, v68
	ds_write2_b32 v0, v35, v39 offset0:68 offset1:84
	ds_write2_b32 v0, v36, v40 offset0:200 offset1:216
	v_add_u32_e32 v0, 0x6800, v68
	ds_write2_b32 v0, v37, v41 offset0:76 offset1:92
	v_lshlrev_b32_e32 v0, 3, v66
	s_waitcnt lgkmcnt(0)
	s_barrier
	v_and_b32_e32 v34, 0x78, v0
	v_or_b32_e32 v0, s18, v34
	v_cmp_gt_i32_e32 vcc, s58, v0
	s_and_saveexec_b64 s[20:21], vcc
	s_cbranch_execz .LBB0_473
	s_ashr_i32 s19, s18, 31
	s_lshl_b64 s[0:1], s[18:19], 1
	s_add_u32 s0, s10, s0
	s_addc_u32 s1, s11, s1
	v_lshlrev_b32_e32 v0, 1, v34
	v_lshl_add_u64 v[42:43], s[0:1], 0, v[0:1]
	v_ashrrev_i32_e32 v0, 4, v66
	v_mul_lo_u32 v35, v0, s92
	v_lshl_add_u32 v44, v34, 2, v35
	s_waitcnt vmcnt(0)
	ds_read_b128 v[34:37], v44
	ds_read_b128 v[38:41], v44 offset:16
	v_add_u32_e32 v0, s17, v0
	s_waitcnt lgkmcnt(1)
	v_cvt_pk_bf16_f32 v34, v34, v35
	v_cvt_pk_bf16_f32 v35, v36, v37
	s_waitcnt lgkmcnt(0)
	v_cvt_pk_bf16_f32 v36, v38, v39
	v_mad_i64_i32 v[38:39], s[0:1], v0, s60, v[42:43]
	v_cvt_pk_bf16_f32 v37, v40, v41
	global_store_dwordx4 v[38:39], v[34:37], off sc1
	ds_read_b128 v[34:37], v44 offset:16896
	ds_read_b128 v[38:41], v44 offset:16912
	s_waitcnt lgkmcnt(1)
	v_cvt_pk_bf16_f32 v34, v34, v35
	v_cvt_pk_bf16_f32 v35, v36, v37
	s_waitcnt lgkmcnt(0)
	v_cvt_pk_bf16_f32 v36, v38, v39
	v_add_u32_e32 v38, 32, v0
	v_mad_i64_i32 v[38:39], s[0:1], v38, s60, v[42:43]
	v_cvt_pk_bf16_f32 v37, v40, v41
	global_store_dwordx4 v[38:39], v[34:37], off sc1
	ds_read_b128 v[34:37], v44 offset:33792
	ds_read_b128 v[38:41], v44 offset:33808
	s_waitcnt lgkmcnt(1)
	v_cvt_pk_bf16_f32 v34, v34, v35
	v_cvt_pk_bf16_f32 v35, v36, v37
	s_waitcnt lgkmcnt(0)
	v_cvt_pk_bf16_f32 v36, v38, v39
	v_add_u32_e32 v38, 64, v0
	v_mad_i64_i32 v[38:39], s[0:1], v38, s60, v[42:43]
	v_cvt_pk_bf16_f32 v37, v40, v41
	global_store_dwordx4 v[38:39], v[34:37], off sc1
	ds_read_b128 v[34:37], v44 offset:50688
	ds_read_b128 v[38:41], v44 offset:50704
	v_add_u32_e32 v0, 0x60, v0
	s_waitcnt lgkmcnt(1)
	v_cvt_pk_bf16_f32 v34, v34, v35
	v_cvt_pk_bf16_f32 v35, v36, v37
	s_waitcnt lgkmcnt(0)
	v_cvt_pk_bf16_f32 v36, v38, v39
	v_mad_i64_i32 v[38:39], s[0:1], v0, s60, v[42:43]
	v_cvt_pk_bf16_f32 v37, v40, v41
	global_store_dwordx4 v[38:39], v[34:37], off sc1
; DI u32x4 pack8(const float* f) { u32x4 o; o.x = pack2(f[0], f[1]); o.y = pack2(f[2], f[3]); o.z = pack2(f[4], f[5]); o.w = pack2(f[6], f[7]); return o; }
; template <int AI, int BJ>
; DI void in_quadrant(PREF p, const f32x4 (&acc)[2][2][4][2], int mt, int nt, float* Cs) {
;     ...
;   if (col0 + 128 > OFF_SV && col0 < OFF_SV + 128) {
;     int b = row0 >> 12, s0 = row0 & 4095;
; #pragma unroll
;     for (int q = 0; q < 4; ++q) {
;       int item = t + 512 * q; int c = item & 127, rg = item >> 7;
;       int vc = col0 + c - OFF_SV;
;       if (vc >= 0 && vc < 128) {
;         float v[8];
; #pragma unroll
;         for (int j = 0; j < 8; ++j) v[j] = Cs[(rg * 8 + j) * CST + c];
;         *(u32x4*)(p.Vst + ((size_t)(b * 2 + (vc >> 6)) * 64 + (vc & 63)) * S_ + s0 + rg * 8) = pack8(v);
;       }
;     }
;   }
.LBB0_473:
	s_or_b64 exec, exec, s[20:21]
	s_cmp_lt_i32 s14, 9
	s_cselect_b64 s[0:1], -1, 0
	s_cmp_eq_u32 s14, 10
	s_cselect_b64 s[20:21], -1, 0
	s_or_b64 s[0:1], s[0:1], s[20:21]
	s_and_b64 vcc, exec, s[0:1]
	s_cbranch_vccnz .LBB0_477
	v_and_b32_e32 v36, 0x7f, v66
	v_or_b32_e32 v0, s18, v36
	v_add_u32_e32 v0, 0xfffff6e0, v0
	v_cmp_gt_u32_e32 vcc, s93, v0
	s_and_saveexec_b64 s[20:21], vcc
	s_cbranch_execz .LBB0_476
	v_lshrrev_b32_e32 v34, 6, v0
	s_ashr_i32 s0, s16, 3
	v_and_or_b32 v34, s0, -2, v34
	v_ashrrev_i32_e32 v35, 31, v34
	v_lshlrev_b64 v[34:35], 19, v[34:35]
	v_lshlrev_b32_e32 v0, 13, v0
	v_lshl_add_u64 v[34:35], s[12:13], 0, v[34:35]
	v_and_b32_e32 v0, 0x7e000, v0
	v_lshl_add_u64 v[34:35], v[34:35], 0, v[0:1]
	v_lshlrev_b32_e32 v0, 2, v36
	v_ashrrev_i32_e32 v36, 4, v66
	s_and_b32 s0, s17, 0xf80
	v_and_b32_e32 v40, -8, v36
	s_lshl_b32 s52, s0, 1
	v_mad_u64_u32 v[42:43], s[0:1], v40, s92, v[0:1]
	v_or_b32_e32 v36, 7, v36
	v_mad_u64_u32 v[44:45], s[0:1], v36, s92, v[0:1]
	ds_read2_b32 v[36:37], v42 offset1:132
	s_waitcnt lgkmcnt(0)
	v_cvt_pk_bf16_f32 v36, v36, v37
	v_add_u32_e32 v37, 0x400, v42
	ds_read2_b32 v[38:39], v37 offset0:8 offset1:140
	s_waitcnt lgkmcnt(0)
	v_cvt_pk_bf16_f32 v37, v38, v39
	v_add_u32_e32 v38, 0x800, v42
	ds_read2_b32 v[38:39], v38 offset0:16 offset1:148
	s_waitcnt lgkmcnt(0)
	v_cvt_pk_bf16_f32 v38, v38, v39
	ds_read_b32 v39, v42 offset:3168
	ds_read_b32 v41, v44
	v_lshl_add_u64 v[34:35], v[34:35], 0, s[52:53]
	s_waitcnt lgkmcnt(0)
	v_cvt_pk_bf16_f32 v39, v39, v41
	v_ashrrev_i32_e32 v41, 31, v40
	v_lshl_add_u64 v[40:41], v[40:41], 1, v[34:35]
	global_store_dwordx4 v[40:41], v[36:39], off sc1
	s_nop 1
	v_add_u32_e32 v36, 0x200, v66
	v_ashrrev_i32_e32 v36, 4, v36
	v_and_b32_e32 v40, -8, v36
	v_mad_u64_u32 v[42:43], s[0:1], v40, s92, v[0:1]
	v_or_b32_e32 v36, 7, v36
	v_mad_u64_u32 v[44:45], s[0:1], v36, s92, v[0:1]
	ds_read2_b32 v[36:37], v42 offset1:132
	s_waitcnt lgkmcnt(0)
	v_cvt_pk_bf16_f32 v36, v36, v37
	v_add_u32_e32 v37, 0x400, v42
	ds_read2_b32 v[38:39], v37 offset0:8 offset1:140
	s_waitcnt lgkmcnt(0)
	v_cvt_pk_bf16_f32 v37, v38, v39
	v_add_u32_e32 v38, 0x800, v42
	ds_read2_b32 v[38:39], v38 offset0:16 offset1:148
	s_waitcnt lgkmcnt(0)
	v_cvt_pk_bf16_f32 v38, v38, v39
	ds_read_b32 v39, v42 offset:3168
	ds_read_b32 v41, v44
	s_waitcnt lgkmcnt(0)
	v_cvt_pk_bf16_f32 v39, v39, v41
	v_ashrrev_i32_e32 v41, 31, v40
	v_lshl_add_u64 v[40:41], v[40:41], 1, v[34:35]
	global_store_dwordx4 v[40:41], v[36:39], off sc1
	s_nop 1
	v_add_u32_e32 v36, 0x400, v66
	v_ashrrev_i32_e32 v36, 4, v36
	v_and_b32_e32 v40, -8, v36
	v_mad_u64_u32 v[42:43], s[0:1], v40, s92, v[0:1]
	v_or_b32_e32 v36, 7, v36
	v_mad_u64_u32 v[44:45], s[0:1], v36, s92, v[0:1]
	ds_read2_b32 v[36:37], v42 offset1:132
	s_waitcnt lgkmcnt(0)
	v_cvt_pk_bf16_f32 v36, v36, v37
	v_add_u32_e32 v37, 0x400, v42
	ds_read2_b32 v[38:39], v37 offset0:8 offset1:140
	s_waitcnt lgkmcnt(0)
	v_cvt_pk_bf16_f32 v37, v38, v39
	v_add_u32_e32 v38, 0x800, v42
	ds_read2_b32 v[38:39], v38 offset0:16 offset1:148
	s_waitcnt lgkmcnt(0)
	v_cvt_pk_bf16_f32 v38, v38, v39
	ds_read_b32 v39, v42 offset:3168
	ds_read_b32 v41, v44
	s_waitcnt lgkmcnt(0)
	v_cvt_pk_bf16_f32 v39, v39, v41
	v_ashrrev_i32_e32 v41, 31, v40
	v_lshl_add_u64 v[40:41], v[40:41], 1, v[34:35]
	global_store_dwordx4 v[40:41], v[36:39], off sc1
	s_nop 1
	v_add_u32_e32 v36, 0x600, v66
	v_ashrrev_i32_e32 v36, 4, v36
	v_and_b32_e32 v40, -8, v36
	v_mad_u64_u32 v[42:43], s[0:1], v40, s92, v[0:1]
	v_or_b32_e32 v36, 7, v36
	v_mad_u64_u32 v[44:45], s[0:1], v36, s92, v[0:1]
	v_add_u32_e32 v0, 0x400, v42
	ds_read2_b32 v[36:37], v42 offset1:132
	ds_read2_b32 v[38:39], v0 offset0:8 offset1:140
	v_add_u32_e32 v0, 0x800, v42
	s_waitcnt lgkmcnt(0)
	v_cvt_pk_bf16_f32 v36, v36, v37
	v_cvt_pk_bf16_f32 v37, v38, v39
	ds_read2_b32 v[38:39], v0 offset0:16 offset1:148
	s_waitcnt lgkmcnt(0)
	v_cvt_pk_bf16_f32 v38, v38, v39
	ds_read_b32 v0, v42 offset:3168
	ds_read_b32 v39, v44
	v_ashrrev_i32_e32 v41, 31, v40
	v_lshl_add_u64 v[34:35], v[40:41], 1, v[34:35]
	s_waitcnt lgkmcnt(0)
	v_cvt_pk_bf16_f32 v39, v0, v39
	global_store_dwordx4 v[34:35], v[36:39], off sc1

; DI u32x4 pack8(const float* f) { u32x4 o; o.x = pack2(f[0], f[1]); o.y = pack2(f[2], f[3]); o.z = pack2(f[4], f[5]); o.w = pack2(f[6], f[7]); return o; }
; DI void lds_barrier() { asm volatile("s_waitcnt lgkmcnt(0)\n\ts_barrier" ::: "memory"); }
; DI int tid512() { int t = threadIdx.x; asm volatile("" : "+v"(t)); return t; }
; template <int AI, int BJ>
; DI void stage_q(const f32x4 (&acc)[2][2][4][2], float* Cs) {
;     ...
;   lds_barrier();
; #pragma unroll
;   for (int m = 0; m < 4; ++m)
; #pragma unroll
;     for (int n = 0; n < 2; ++n)
; #pragma unroll
;       for (int j = 0; j < 4; ++j) Cs[(wr * 64 + m * 16 + fq * 4 + j) * CST + wc * 32 + n * 16 + fr] = acc[AI][BJ][m][n][j];
;   lds_barrier();
; template <int AI, int BJ>
; DI void in_quadrant(PREF p, const f32x4 (&acc)[2][2][4][2], int mt, int nt, float* Cs) {
;   const int t = tid512();
;   const int row0 = mt * 256 + AI * 128, col0 = nt * 256 + BJ * 128;
;   if (col0 >= HW) return;
;   stage_q<AI, BJ>(acc, Cs);
; #pragma unroll
;   for (int q = 0; q < 4; ++q) {
;     int r = (t >> 4) + 32 * q, c = (t & 15) * 8;
;     if (col0 + c < HW) {
;       float v[8]; ld8(Cs + r * CST + c, v);
;       *(u32x4*)(p.hb + (size_t)(row0 + r) * HW + col0 + c) = pack8(v);
;     }
;   }
.LBB0_477:
	v_mov_b32_e32 v34, v168
	s_andn2_b64 vcc, exec, s[22:23]
	s_cbranch_vccnz .LBB0_445
	v_mov_b32_e32 v0, v168
	s_waitcnt lgkmcnt(0)
	s_barrier
	s_nop 0
	v_and_b32_e32 v35, 15, v0
	v_lshrrev_b32_e32 v36, 2, v0
	v_lshlrev_b32_e32 v0, 1, v0
	v_lshlrev_b32_e32 v35, 2, v35
	v_and_b32_e32 v36, 0xfffffcc, v36
	v_and_or_b32 v0, v0, s89, v35
	v_mad_u64_u32 v[36:37], s[0:1], v36, s92, v[0:1]
	v_add_u32_e32 v0, 0x400, v36
	ds_write2_b32 v36, v22, v30 offset1:16
	ds_write2_b32 v36, v23, v31 offset0:132 offset1:148
	ds_write2_b32 v0, v24, v32 offset0:8 offset1:24
	ds_write2_b32 v0, v25, v33 offset0:140 offset1:156
	v_add_u32_e32 v0, 0x2000, v36
	ds_write2_b32 v0, v18, v26 offset0:64 offset1:80
	ds_write2_b32 v0, v19, v27 offset0:196 offset1:212
	v_add_u32_e32 v0, 0x2400, v36
	ds_write2_b32 v0, v20, v28 offset0:72 offset1:88
	ds_write2_b32 v0, v21, v29 offset0:204 offset1:220
	v_add_u32_e32 v0, 0x4000, v36
	ds_write2_b32 v0, v10, v14 offset0:128 offset1:144
	v_add_u32_e32 v0, 0x4400, v36
	ds_write2_b32 v0, v11, v15 offset0:4 offset1:20
	ds_write2_b32 v0, v12, v16 offset0:136 offset1:152
	v_add_u32_e32 v0, 0x4800, v36
	ds_write2_b32 v0, v13, v17 offset0:12 offset1:28
	v_add_u32_e32 v0, 0x6000, v36
	ds_write2_b32 v0, v2, v6 offset0:192 offset1:208
	v_add_u32_e32 v0, 0x6400, v36
	ds_write2_b32 v0, v3, v7 offset0:68 offset1:84
	ds_write2_b32 v0, v4, v8 offset0:200 offset1:216
	v_add_u32_e32 v0, 0x6800, v36
	ds_write2_b32 v0, v5, v9 offset0:76 offset1:92
	v_lshlrev_b32_e32 v0, 3, v34
	s_waitcnt lgkmcnt(0)
	s_barrier
	v_and_b32_e32 v2, 0x78, v0
	v_or_b32_e32 v0, s15, v2
	v_cmp_gt_i32_e32 vcc, s58, v0
	s_and_saveexec_b64 s[20:21], vcc
	s_cbranch_execz .LBB0_480
	s_ashr_i32 s19, s18, 31
	s_lshl_b64 s[0:1], s[18:19], 1
	s_add_u32 s0, s10, s0
	s_addc_u32 s1, s11, s1
	v_lshlrev_b32_e32 v0, 1, v2
	v_lshl_add_u64 v[10:11], s[0:1], 0, v[0:1]
	v_ashrrev_i32_e32 v0, 4, v34
	v_mul_lo_u32 v3, v0, s92
	v_lshl_add_u32 v12, v2, 2, v3
	s_waitcnt vmcnt(0)
	ds_read_b128 v[2:5], v12
	ds_read_b128 v[6:9], v12 offset:16
	v_add_u32_e32 v0, s17, v0
	s_waitcnt lgkmcnt(1)
	v_cvt_pk_bf16_f32 v2, v2, v3
	v_cvt_pk_bf16_f32 v3, v4, v5
	s_waitcnt lgkmcnt(0)
	v_cvt_pk_bf16_f32 v4, v6, v7
	v_mad_i64_i32 v[6:7], s[0:1], v0, s60, v[10:11]
	v_cvt_pk_bf16_f32 v5, v8, v9
	global_store_dwordx4 v[6:7], v[2:5], off offset:256 sc1
	ds_read_b128 v[2:5], v12 offset:16896
	ds_read_b128 v[6:9], v12 offset:16912
	s_waitcnt lgkmcnt(1)
	v_cvt_pk_bf16_f32 v2, v2, v3
	v_cvt_pk_bf16_f32 v3, v4, v5
	s_waitcnt lgkmcnt(0)
	v_cvt_pk_bf16_f32 v4, v6, v7
	v_add_u32_e32 v6, 32, v0
	v_mad_i64_i32 v[6:7], s[0:1], v6, s60, v[10:11]
	v_cvt_pk_bf16_f32 v5, v8, v9
	global_store_dwordx4 v[6:7], v[2:5], off offset:256 sc1
	ds_read_b128 v[2:5], v12 offset:33792
	ds_read_b128 v[6:9], v12 offset:33808
	s_waitcnt lgkmcnt(1)
	v_cvt_pk_bf16_f32 v2, v2, v3
	v_cvt_pk_bf16_f32 v3, v4, v5
	s_waitcnt lgkmcnt(0)
	v_cvt_pk_bf16_f32 v4, v6, v7
	v_add_u32_e32 v6, 64, v0
	v_mad_i64_i32 v[6:7], s[0:1], v6, s60, v[10:11]
	v_cvt_pk_bf16_f32 v5, v8, v9
	global_store_dwordx4 v[6:7], v[2:5], off offset:256 sc1
	ds_read_b128 v[2:5], v12 offset:50688
	ds_read_b128 v[6:9], v12 offset:50704
	v_add_u32_e32 v0, 0x60, v0
	s_waitcnt lgkmcnt(1)
	v_cvt_pk_bf16_f32 v2, v2, v3
	v_cvt_pk_bf16_f32 v3, v4, v5
	s_waitcnt lgkmcnt(0)
	v_cvt_pk_bf16_f32 v4, v6, v7
	v_mad_i64_i32 v[6:7], s[0:1], v0, s60, v[10:11]
	v_cvt_pk_bf16_f32 v5, v8, v9
	global_store_dwordx4 v[6:7], v[2:5], off offset:256 sc1
; DI u32x4 pack8(const float* f) { u32x4 o; o.x = pack2(f[0], f[1]); o.y = pack2(f[2], f[3]); o.z = pack2(f[4], f[5]); o.w = pack2(f[6], f[7]); return o; }
; template <int AI, int BJ>
; DI void in_quadrant(PREF p, const f32x4 (&acc)[2][2][4][2], int mt, int nt, float* Cs) {
;     ...
;   if (col0 + 128 > OFF_SV && col0 < OFF_SV + 128) {
;     int b = row0 >> 12, s0 = row0 & 4095;
; #pragma unroll
;     for (int q = 0; q < 4; ++q) {
;       int item = t + 512 * q; int c = item & 127, rg = item >> 7;
;       int vc = col0 + c - OFF_SV;
;       if (vc >= 0 && vc < 128) {
;         float v[8];
; #pragma unroll
;         for (int j = 0; j < 8; ++j) v[j] = Cs[(rg * 8 + j) * CST + c];
;         *(u32x4*)(p.Vst + ((size_t)(b * 2 + (vc >> 6)) * 64 + (vc & 63)) * S_ + s0 + rg * 8) = pack8(v);
;       }
;     }
;   }
.LBB0_480:
	s_or_b64 exec, exec, s[20:21]
	s_cmp_lt_i32 s14, 9
	s_cselect_b64 s[0:1], -1, 0
	s_cmpk_gt_i32 s15, 0x99f
	s_cselect_b64 s[18:19], -1, 0
	s_or_b64 s[0:1], s[0:1], s[18:19]
	s_and_b64 vcc, exec, s[0:1]
	s_cbranch_vccnz .LBB0_445
	v_and_b32_e32 v4, 0x7f, v34
	v_or_b32_e32 v0, s15, v4
	v_add_u32_e32 v0, 0xfffff6e0, v0
	v_cmp_gt_u32_e32 vcc, s93, v0
	s_and_saveexec_b64 s[18:19], vcc
	s_cbranch_execz .LBB0_444
	v_lshrrev_b32_e32 v2, 6, v0
	s_ashr_i32 s0, s16, 3
	v_and_or_b32 v2, s0, -2, v2
	v_ashrrev_i32_e32 v3, 31, v2
	v_lshlrev_b64 v[2:3], 19, v[2:3]
	v_lshlrev_b32_e32 v0, 13, v0
	v_lshl_add_u64 v[2:3], s[12:13], 0, v[2:3]
	v_and_b32_e32 v0, 0x7e000, v0
	v_lshl_add_u64 v[2:3], v[2:3], 0, v[0:1]
	v_lshlrev_b32_e32 v0, 2, v4
	v_ashrrev_i32_e32 v4, 4, v34
	s_and_b32 s0, s17, 0xf80
	v_and_b32_e32 v8, -8, v4
	s_lshl_b32 s52, s0, 1
	v_mad_u64_u32 v[10:11], s[0:1], v8, s92, v[0:1]
	v_or_b32_e32 v4, 7, v4
	v_mad_u64_u32 v[12:13], s[0:1], v4, s92, v[0:1]
	ds_read2_b32 v[4:5], v10 offset1:132
	s_waitcnt lgkmcnt(0)
	v_cvt_pk_bf16_f32 v4, v4, v5
	v_add_u32_e32 v5, 0x400, v10
	ds_read2_b32 v[6:7], v5 offset0:8 offset1:140
	s_waitcnt lgkmcnt(0)
	v_cvt_pk_bf16_f32 v5, v6, v7
	v_add_u32_e32 v6, 0x800, v10
	ds_read2_b32 v[6:7], v6 offset0:16 offset1:148
	s_waitcnt lgkmcnt(0)
	v_cvt_pk_bf16_f32 v6, v6, v7
	ds_read_b32 v7, v10 offset:3168
	ds_read_b32 v9, v12
	v_lshl_add_u64 v[2:3], v[2:3], 0, s[52:53]
	s_waitcnt lgkmcnt(0)
	v_cvt_pk_bf16_f32 v7, v7, v9
	v_ashrrev_i32_e32 v9, 31, v8
	v_lshl_add_u64 v[8:9], v[8:9], 1, v[2:3]
	global_store_dwordx4 v[8:9], v[4:7], off sc1
	s_nop 1
	v_add_u32_e32 v4, 0x200, v34
	v_ashrrev_i32_e32 v4, 4, v4
	v_and_b32_e32 v8, -8, v4
	v_mad_u64_u32 v[10:11], s[0:1], v8, s92, v[0:1]
	v_or_b32_e32 v4, 7, v4
	v_mad_u64_u32 v[12:13], s[0:1], v4, s92, v[0:1]
	ds_read2_b32 v[4:5], v10 offset1:132
	s_waitcnt lgkmcnt(0)
	v_cvt_pk_bf16_f32 v4, v4, v5
	v_add_u32_e32 v5, 0x400, v10
	ds_read2_b32 v[6:7], v5 offset0:8 offset1:140
	s_waitcnt lgkmcnt(0)
	v_cvt_pk_bf16_f32 v5, v6, v7
	v_add_u32_e32 v6, 0x800, v10
	ds_read2_b32 v[6:7], v6 offset0:16 offset1:148
	s_waitcnt lgkmcnt(0)
	v_cvt_pk_bf16_f32 v6, v6, v7
	ds_read_b32 v7, v10 offset:3168
	ds_read_b32 v9, v12
	s_waitcnt lgkmcnt(0)
	v_cvt_pk_bf16_f32 v7, v7, v9
	v_ashrrev_i32_e32 v9, 31, v8
	v_lshl_add_u64 v[8:9], v[8:9], 1, v[2:3]
	global_store_dwordx4 v[8:9], v[4:7], off sc1
	s_nop 1
	v_add_u32_e32 v4, 0x400, v34
	v_ashrrev_i32_e32 v4, 4, v4
	v_and_b32_e32 v8, -8, v4
	v_mad_u64_u32 v[10:11], s[0:1], v8, s92, v[0:1]
	v_or_b32_e32 v4, 7, v4
	v_mad_u64_u32 v[12:13], s[0:1], v4, s92, v[0:1]
	ds_read2_b32 v[4:5], v10 offset1:132
	s_waitcnt lgkmcnt(0)
	v_cvt_pk_bf16_f32 v4, v4, v5
	v_add_u32_e32 v5, 0x400, v10
	ds_read2_b32 v[6:7], v5 offset0:8 offset1:140
	s_waitcnt lgkmcnt(0)
	v_cvt_pk_bf16_f32 v5, v6, v7
	v_add_u32_e32 v6, 0x800, v10
	ds_read2_b32 v[6:7], v6 offset0:16 offset1:148
	s_waitcnt lgkmcnt(0)
	v_cvt_pk_bf16_f32 v6, v6, v7
	ds_read_b32 v7, v10 offset:3168
	ds_read_b32 v9, v12
	s_waitcnt lgkmcnt(0)
	v_cvt_pk_bf16_f32 v7, v7, v9
	v_ashrrev_i32_e32 v9, 31, v8
	v_lshl_add_u64 v[8:9], v[8:9], 1, v[2:3]
	global_store_dwordx4 v[8:9], v[4:7], off sc1
	s_nop 1
	v_add_u32_e32 v4, 0x600, v34
	v_ashrrev_i32_e32 v4, 4, v4
	v_and_b32_e32 v8, -8, v4
	v_mad_u64_u32 v[10:11], s[0:1], v8, s92, v[0:1]
	v_or_b32_e32 v4, 7, v4
	v_mad_u64_u32 v[12:13], s[0:1], v4, s92, v[0:1]
	v_add_u32_e32 v0, 0x400, v10
	ds_read2_b32 v[4:5], v10 offset1:132
	ds_read2_b32 v[6:7], v0 offset0:8 offset1:140
	v_add_u32_e32 v0, 0x800, v10
	s_waitcnt lgkmcnt(0)
	v_cvt_pk_bf16_f32 v4, v4, v5
	v_cvt_pk_bf16_f32 v5, v6, v7
	ds_read2_b32 v[6:7], v0 offset0:16 offset1:148
	s_waitcnt lgkmcnt(0)
	v_cvt_pk_bf16_f32 v6, v6, v7
	ds_read_b32 v0, v10 offset:3168
	ds_read_b32 v7, v12
	v_ashrrev_i32_e32 v9, 31, v8
	v_lshl_add_u64 v[2:3], v[8:9], 1, v[2:3]
	s_waitcnt lgkmcnt(0)
	v_cvt_pk_bf16_f32 v7, v0, v7
	global_store_dwordx4 v[2:3], v[4:7], off sc1
	s_branch .LBB0_444
